# SB attention: 2 static items per wave instead of 4, remaining 8192 items through the per-XCD dynamic queues (1024 per XCD)
# baseline (speedup 1.0000x reference)
; __device__ __forceinline__ void sb_item(const bf16_t* hbuf, const float* kmax2, bf16_t* mixed, LAS bf16_t* vT, int item, int lane) {
;     ...
;                 const int m = 16 * mt + r; unsigned tw[4];
; #pragma unroll
;                 for (int p = 0; p < 4; ++p) { const int i0 = 2 * p, i1 = 2 * p + 1;
;                     const int ma = 32 * mb + (i0 < 4 ? 4 * q + i0 : 16 + 4 * q + i0 - 4), mbb = 32 * mb + (i1 < 4 ? 4 * q + i1 : 16 + 4 * q + i1 - 4);
;                     tw[p] = (ma >= m ? 0x3f80u : 0u) | (mbb >= m ? 0x3f800000u : 0u); }
;                 const bf16x8 tri = as_bf16x8((u32x4){tw[0], tw[1], tw[2], tw[3]});
; __device__ __forceinline__ void run_phase(const Args& a, const int ph, LAS unsigned char* lds, const int tid, const int rpt) {
;     ...
;                       const int nstat = (4 * NGW <= 12 * 1024) ? 4 * NGW : 0;
;                       if (nstat) for (int it = 4 * gw; it < 4 * gw + 4; ++it) sb_item(hbuf, kmax2, mixed, vT, it, lane);
.LBB0_230:
.LBB0_231:
	v_readlane_b32 s1, v249, 49
	s_lshl_b32 s0, s1, 4
	s_cmpk_lt_i32 s1, 0x181
	s_cselect_b32 s0, s0, 0
	s_cmp_lg_u32 s0, 0
	v_writelane_b32 v249, s0, 54
	s_cbranch_scc0 .LBB0_552
	v_lshrrev_b32_e32 v0, 4, v248
	v_and_b32_e32 v122, 15, v168
	v_lshlrev_b32_e32 v120, 2, v0
	v_lshlrev_b32_e32 v1, 2, v248
	v_or_b32_e32 v143, 1, v120
	v_cmp_lt_u32_e32 vcc, v120, v122
	v_mov_b32_e32 v7, 0x3f80
	v_lshlrev_b32_e32 v124, 3, v0
	v_xor_b32_e32 v132, 64, v1
	v_xor_b32_e32 v133, 0x80, v1
	v_and_b32_e32 v1, 7, v168
	v_cndmask_b32_e64 v0, v7, 0, vcc
	v_cmp_lt_u32_e32 vcc, v143, v122
	v_or_b32_e32 v144, 2, v120
	v_lshrrev_b32_e32 v134, 3, v248
	v_lshlrev_b32_e32 v126, 3, v1
	v_mul_u32_u24_e32 v139, 0x440, v1
	v_cndmask_b32_e64 v1, 1.0, 0, vcc
	v_or_b32_e32 v145, 3, v120
	v_cmp_lt_u32_e32 vcc, v144, v122
	v_lshlrev_b32_e32 v2, 1, v134
	v_readlane_b32 s0, v249, 53
	v_or_b32_e32 v36, v1, v0
	v_cndmask_b32_e64 v1, v7, 0, vcc
	v_cmp_lt_u32_e32 vcc, v145, v122
	v_or_b32_e32 v140, 17, v120
	v_or_b32_e32 v146, 16, v122
	v_add3_u32 v151, s0, v2, v139
	v_cndmask_b32_e64 v2, 1.0, 0, vcc
	v_or_b32_e32 v141, 18, v120
	v_cmp_lt_u32_e32 vcc, v140, v146
	v_or_b32_e32 v37, v2, v1
	v_or_b32_e32 v142, 19, v120
	v_cndmask_b32_e64 v1, 1.0, 0, vcc
	v_cmp_lt_u32_e32 vcc, v141, v146
	v_or_b32_e32 v8, 48, v248
	v_or_b32_e32 v136, 16, v120
	v_or_b32_e32 v2, v1, v0
	v_cndmask_b32_e64 v0, v7, 0, vcc
	v_cmp_lt_u32_e32 vcc, v142, v146
	v_subrev_u32_e32 v147, 32, v8
	s_lshl_b32 s12, s16, 1
	v_cndmask_b32_e64 v1, 1.0, 0, vcc
	v_cmp_lt_u32_e32 vcc, v136, v147
	v_add_u32_e32 v152, s0, v124
	s_movk_i32 s0, 0x88
	v_cndmask_b32_e64 v4, v7, 0, vcc
	v_cmp_lt_u32_e32 vcc, v140, v147
	s_waitcnt vmcnt(0)
	v_mov_b32_e32 v9, 0x880
	v_mov_b32_e32 v123, v33
	v_cndmask_b32_e64 v5, 1.0, 0, vcc
	v_cmp_lt_u32_e32 vcc, v141, v147
	v_or_b32_e32 v6, v5, v4
	v_mov_b32_e32 v125, v33
	v_cndmask_b32_e64 v4, v7, 0, vcc
	v_cmp_lt_u32_e32 vcc, v142, v147
	v_mov_b32_e32 v127, v33
	v_lshlrev_b32_e32 v135, 2, v122
	v_cndmask_b32_e64 v5, 1.0, 0, vcc
	v_mov_b32_e32 v39, v38
	v_or_b32_e32 v3, v1, v0
	v_mov_b32_e32 v0, v33
	v_mov_b32_e32 v1, v33
	v_or_b32_e32 v7, v5, v4
	v_mov_b32_e32 v4, v33
	v_mov_b32_e32 v5, v33
	v_mul_u32_u24_e32 v148, 0x88, v122
	v_mad_u32_u24 v149, v122, s0, v9
	v_mul_u32_u24_e32 v150, 0x88, v8
	v_or_b32_e32 v137, 32, v120
	v_or_b32_e32 v138, 48, v120
	v_mov_b32_e32 v121, v33
	s_or_b32 s15, s12, 1
	s_branch .LBB0_234

; __device__ __forceinline__ float bflo(unsigned u) { return __uint_as_float(u << 16); }
; __device__ __forceinline__ float bfhi(unsigned u) { return __uint_as_float(u & 0xffff0000u); }
; __device__ __forceinline__ float sx(float v, int m, int lane) { return __builtin_bit_cast(float, __builtin_amdgcn_ds_bpermute((lane ^ m) << 2, __builtin_bit_cast(int, v))); }
; __device__ __forceinline__ void sb_item(const bf16_t* hbuf, const float* kmax2, bf16_t* mixed, LAS bf16_t* vT, int item, int lane) {
;     const int bh = item >> 10, qt = item & 1023, b = bh / 6, h = bh % 6, tq0 = qt * 16; const size_t row0 = (size_t)b * SEQ + tq0;
;     const int r = lane & 15, q = lane >> 4;
;     bf16x8 qf[2]; float bound, carry = 0.f;
;     const float km2 = kmax2[bh];
;     { float s = 0.f;
; #pragma unroll
;       for (int ks = 0; ks < 2; ++ks) { const u32x4 v = *(const u32x4*)(hbuf + (row0 + r) * INWP + C_SBQ + h * 64 + 32 * ks + 8 * q); qf[ks] = as_bf16x8(v);
;           s += bflo(v.x) * bflo(v.x) + bfhi(v.x) * bfhi(v.x) + bflo(v.y) * bflo(v.y) + bfhi(v.y) * bfhi(v.y) + bflo(v.z) * bflo(v.z) + bfhi(v.z) * bfhi(v.z) + bflo(v.w) * bflo(v.w) + bfhi(v.w) * bfhi(v.w); }
;       s += sx(s, 16, lane); s += sx(s, 32, lane);
;       bound = sqrtf(s * km2) * 0.125f * 1.01f + 0.05f; }
;     const int qpos = tq0 + r;
;     f32x4 O[4];
; #pragma unroll
;     for (int et = 0; et < 4; ++et) O[et] = (f32x4){0.f, 0.f, 0.f, 0.f};
;     const int cr = lane >> 3, dc = lane & 7;
;     const bf16_t* seqp = hbuf + (size_t)b * SEQ * INWP + h * 64;
;     u32x4 vreg[8], kreg[8];
;     { const int k0 = tq0 + 16 - 64;
; #pragma unroll
;       for (int i = 0; i < 8; ++i) vreg[i] = *(const u32x4*)(seqp + (size_t)max(k0 + cr + 8 * i, 0) * INWP + C_SBV + 8 * dc);
; #pragma unroll
;       for (int i = 0; i < 8; ++i) kreg[i] = *(const u32x4*)(seqp + (size_t)max(k0 + 16 * (i >> 1) + r, 0) * INWP + C_SBK + 32 * (i & 1) + 8 * q); }
.LBB0_234:
	s_and_b32 s98, s12, 1
	s_lshl_b32 s98, s98, 3
	s_bfe_u32 s99, s12, 0x30001
	s_add_i32 s98, s98, s99
	s_and_b32 s99, s12, 0xfffffff0
	s_or_b32 s98, s98, s99
	s_ashr_i32 s0, s98, 10
	s_mul_hi_i32 s1, s0, 0x2aaaaaab
	s_lshr_b32 s17, s1, 31
	s_add_i32 s20, s1, s17
	s_mul_i32 s1, s20, 6
	s_sub_i32 s17, s0, s1
	s_lshl_b32 s1, s98, 4
	s_ashr_i32 s21, s20, 31
	s_and_b32 s26, s1, 0x3ff0
	s_lshl_b64 s[22:23], s[20:21], 14
	s_ashr_i32 s1, s0, 31
	s_or_b32 s21, s22, s26
	s_lshl_b64 s[0:1], s[0:1], 2
	s_add_u32 s0, s75, s0
	s_addc_u32 s1, s74, s1
	v_or_b32_e32 v34, s21, v122
	v_mov_b64_e32 v[8:9], s[42:43]
	s_lshl_b32 s72, s17, 6
	global_load_dword v214, v33, s[0:1] offset:1024
	v_mad_u64_u32 v[8:9], s[0:1], v34, s5, v[8:9]
	s_ashr_i32 s73, s72, 31
	v_mov_b32_e32 v35, s23
	v_mad_i32_i24 v9, s23, v207, v9
	s_lshl_b64 s[22:23], s[72:73], 1
	v_lshl_add_u64 v[8:9], v[8:9], 0, s[22:23]
	v_lshlrev_b32_e32 v32, 1, v124
	v_lshl_add_u64 v[12:13], v[8:9], 0, v[32:33]
	global_load_dwordx4 v[8:11], v[12:13], off offset:512
	v_lshlrev_b32_e32 v88, 1, v126
	v_mov_b32_e32 v89, v33
	v_mov_b32_e32 v153, 0
	v_or_b32_e32 v155, s26, v122
	v_mov_b32_e32 v100, 0
	v_mov_b32_e32 v101, v153
	v_mov_b32_e32 v102, v153
	v_mov_b32_e32 v103, v153
	v_mov_b32_e32 v96, 0
	v_mov_b32_e32 v97, v153
	v_mov_b32_e32 v98, v153
	v_mov_b32_e32 v99, v153
	v_mov_b32_e32 v92, 0
	v_mov_b32_e32 v93, v153
	v_mov_b32_e32 v94, v153
	v_mov_b32_e32 v95, v153
	v_mov_b32_e32 v90, v153
	v_mov_b32_e32 v91, v153
	global_load_dwordx4 v[12:15], v[12:13], off offset:576
	s_waitcnt vmcnt(7)
	s_mul_i32 s1, s20, 0x6000000
	s_mul_hi_i32 s0, s20, 0x6000000
	s_add_u32 s1, s42, s1
	s_addc_u32 s17, s43, s0
	s_add_u32 s0, s1, s22
	s_addc_u32 s1, s17, s23
	s_sub_i32 s17, s26, 48
	v_or_b32_e32 v48, s17, v122
	v_or_b32_e32 v86, s17, v134
	v_max_i32_e32 v16, 0xffffffd0, v48
	v_max_i32_e32 v24, 0xffffffe0, v48
	v_max_i32_e32 v40, -16, v48
	v_max_i32_e32 v64, 0xffffffd8, v86
	v_max_i32_e32 v68, 0xffffffe0, v86
	v_add_u32_e32 v16, 48, v16
	v_mov_b64_e32 v[84:85], s[0:1]
	v_add_u32_e32 v24, 32, v24
	v_add_u32_e32 v40, 16, v40
	v_max_i32_e32 v48, 0, v48
	v_add_u32_e32 v64, 40, v64
	v_add_u32_e32 v68, 32, v68
	v_mad_u64_u32 v[16:17], s[20:21], v16, s5, v[84:85]
	v_mad_u64_u32 v[24:25], s[20:21], v24, s5, v[84:85]
	v_mad_u64_u32 v[40:41], s[20:21], v40, s5, v[84:85]
	v_mad_u64_u32 v[48:49], s[20:21], v48, s5, v[84:85]
	v_mad_u64_u32 v[64:65], s[20:21], v64, s5, v[84:85]
	v_mad_u64_u32 v[68:69], s[20:21], v68, s5, v[84:85]
	v_lshl_add_u64 v[20:21], v[16:17], 0, v[32:33]
	v_lshl_add_u64 v[28:29], v[24:25], 0, v[32:33]
	v_lshl_add_u64 v[44:45], v[40:41], 0, v[32:33]
	v_lshl_add_u64 v[52:53], v[48:49], 0, v[32:33]
	v_lshl_add_u64 v[64:65], v[64:65], 0, v[88:89]
	v_lshl_add_u64 v[68:69], v[68:69], 0, v[88:89]
	global_load_dwordx4 v[16:19], v[20:21], off offset:1344
	s_nop 0
	global_load_dwordx4 v[20:23], v[20:21], off offset:1280
	s_nop 0
	global_load_dwordx4 v[24:27], v[28:29], off offset:1344
	s_nop 0
	global_load_dwordx4 v[28:31], v[28:29], off offset:1280
	s_nop 0
	global_load_dwordx4 v[40:43], v[44:45], off offset:1344
	s_nop 0
	global_load_dwordx4 v[44:47], v[44:45], off offset:1280
	s_nop 0
	global_load_dwordx4 v[48:51], v[52:53], off offset:1344
	s_nop 0
	global_load_dwordx4 v[52:55], v[52:53], off offset:1280
	v_max_i32_e32 v76, -16, v86
	global_load_dwordx4 v[64:67], v[64:65], off offset:2048
	v_add_u32_e32 v76, 16, v76
	global_load_dwordx4 v[72:75], v[68:69], off offset:2048
	v_max_i32_e32 v68, 0xffffffe8, v86
	v_add_u32_e32 v68, 24, v68
	v_mad_u64_u32 v[68:69], s[20:21], v68, s5, v[84:85]
	v_mad_u64_u32 v[76:77], s[20:21], v76, s5, v[84:85]
	v_lshl_add_u64 v[68:69], v[68:69], 0, v[88:89]
	v_lshl_add_u64 v[76:77], v[76:77], 0, v[88:89]
	v_max_i32_e32 v56, 0xffffffc8, v86
	v_max_i32_e32 v60, 0xffffffd0, v86
	global_load_dwordx4 v[68:71], v[68:69], off offset:2048
	v_add_u32_e32 v56, 56, v56
	global_load_dwordx4 v[80:83], v[76:77], off offset:2048
	v_or_b32_e32 v76, 8, v86
	v_add_u32_e32 v60, 48, v60
	v_max_i32_e32 v76, 0, v76
	v_max_i32_e32 v86, 0, v86
	v_mad_u64_u32 v[56:57], s[20:21], v56, s5, v[84:85]
	v_mad_u64_u32 v[60:61], s[20:21], v60, s5, v[84:85]
	v_mad_u64_u32 v[76:77], s[20:21], v76, s5, v[84:85]
	v_mad_u64_u32 v[84:85], s[20:21], v86, s5, v[84:85]
	v_lshl_add_u64 v[56:57], v[56:57], 0, v[88:89]
	v_lshl_add_u64 v[60:61], v[60:61], 0, v[88:89]
	v_lshl_add_u64 v[76:77], v[76:77], 0, v[88:89]
	v_lshl_add_u64 v[84:85], v[84:85], 0, v[88:89]
	global_load_dwordx4 v[56:59], v[56:57], off offset:2048
	v_lshl_add_u64 v[128:129], s[0:1], 0, v[88:89]
	global_load_dwordx4 v[60:63], v[60:61], off offset:2048
	v_lshl_add_u64 v[130:131], s[0:1], 0, v[32:33]
	global_load_dwordx4 v[76:79], v[76:77], off offset:2048
	v_mov_b32_e32 v88, 0
	global_load_dwordx4 v[84:87], v[84:85], off offset:2048
	v_mov_b32_e32 v89, v153
	s_mov_b32 s98, 0xf800000
	s_waitcnt vmcnt(16)
	v_and_b32_e32 v216, 0xffff0000, v8
	v_lshlrev_b32_e32 v215, 16, v8
	v_mul_f32_e32 v217, v216, v216
	v_fmac_f32_e32 v217, v215, v215
	v_lshlrev_b32_e32 v215, 16, v9
	v_fmac_f32_e32 v217, v215, v215
	v_and_b32_e32 v215, 0xffff0000, v9
	v_fmac_f32_e32 v217, v215, v215
	v_lshlrev_b32_e32 v215, 16, v10
	v_fmac_f32_e32 v217, v215, v215
	v_and_b32_e32 v215, 0xffff0000, v10
	v_fmac_f32_e32 v217, v215, v215
	v_lshlrev_b32_e32 v215, 16, v11
	v_fmac_f32_e32 v217, v215, v215
	v_and_b32_e32 v215, 0xffff0000, v11
	v_fmac_f32_e32 v217, v215, v215
	v_and_b32_e32 v219, 0xffff0000, v12
	v_lshlrev_b32_e32 v218, 16, v12
	v_mul_f32_e32 v219, v219, v219
	v_fmac_f32_e32 v219, v218, v218
	v_lshlrev_b32_e32 v218, 16, v13
	v_fmac_f32_e32 v219, v218, v218
	v_and_b32_e32 v218, 0xffff0000, v13
	v_fmac_f32_e32 v219, v218, v218
	v_lshlrev_b32_e32 v218, 16, v14
	v_fmac_f32_e32 v219, v218, v218
	v_and_b32_e32 v218, 0xffff0000, v14
	v_fmac_f32_e32 v219, v218, v218
	v_lshlrev_b32_e32 v218, 16, v15
	v_fmac_f32_e32 v219, v218, v218
	v_and_b32_e32 v218, 0xffff0000, v15
	v_fmac_f32_e32 v219, v218, v218
	v_add_f32_e32 v217, v217, v219
	ds_bpermute_b32 v218, v132, v217
	s_waitcnt lgkmcnt(0)
	v_add_f32_e32 v217, v217, v218
	ds_bpermute_b32 v218, v133, v217
	s_waitcnt lgkmcnt(0)
	v_add_f32_e32 v217, v217, v218
	v_mul_f32_e32 v214, v214, v217
	v_cmp_gt_f32_e32 vcc, s98, v214
	v_mul_f32_e32 v217, 0x4f800000, v214
	s_nop 0
	v_cndmask_b32_e32 v214, v214, v217, vcc
	v_sqrt_f32_e32 v217, v214
	s_nop 0
	v_add_u32_e32 v218, -1, v217
	v_fma_f32 v219, -v218, v217, v214
	v_cmp_ge_f32_e64 s[100:101], 0, v219
	v_add_u32_e32 v219, 1, v217
	s_nop 0
	v_cndmask_b32_e64 v218, v217, v218, s[100:101]
	v_fma_f32 v217, -v219, v217, v214
	v_cmp_lt_f32_e64 s[100:101], 0, v217
	s_nop 1
	v_cndmask_b32_e64 v217, v218, v219, s[100:101]
	v_mul_f32_e32 v218, 0x37800000, v217
	v_cndmask_b32_e32 v217, v217, v218, vcc
	v_cmp_class_f32_e32 vcc, v214, v209
	v_cndmask_b32_e32 v214, v217, v214, vcc
	v_mul_f32_e32 v214, 0x3e000000, v214
	v_fmamk_f32 v154, v214, 0x3f8147ae, v170
	s_branch .LBB0_236

; __device__ __forceinline__ void run_phase(const Args& a, const int ph, LAS unsigned char* lds, const int tid, const int rpt) {
;     ...
;                       for (;;) { int it0 = 0; if (lane == 0) it0 = (int)atomicAdd(qctr, 2u); it0 = nstat + __builtin_amdgcn_readfirstlane(it0); if (it0 >= 12 * 1024) break;
;                           for (int it = it0; it < it0 + 2; ++it) sb_item(hbuf, kmax2, mixed, vT, it, lane); } }
.LBB0_281:
	s_or_b64 exec, exec, s[0:1]
	v_readfirstlane_b32 s12, v4
	v_readlane_b32 s98, v249, 49
	s_nop 0
	s_cmp_eq_u32 s98, 0x100
	s_cbranch_scc0 .Lxq_skip_b
	s_cmp_ge_u32 s12, 0x400
	s_cselect_b32 s12, 0x10000, s12
	v_readlane_b32 s98, v251, 37
	s_lshl_b32 s98, s98, 10
	s_add_i32 s12, s12, s98
